# XCD-local seams: workgroup-scope L1 invalidate (buffer_inv sc0) instead of agent-scope
# speedup vs baseline: 1.0054x; 1.0023x over previous
; __device__ __forceinline__ unsigned xb_ld(unsigned* p)              { return __hip_atomic_load(p, __ATOMIC_RELAXED, __HIP_MEMORY_SCOPE_AGENT); }
; __device__ __forceinline__ unsigned xb_add(unsigned* p, unsigned v) { return __hip_atomic_fetch_add(p, v, __ATOMIC_RELAXED, __HIP_MEMORY_SCOPE_AGENT); }
; __device__ __forceinline__ void xcd_local_barrier(unsigned* xl, unsigned x) {
;     ...
;         const unsigned old = xb_add(sub, 1u), g = old / 32u;
;         if (old + 1u == (g + 1u) * 32u) (void)xb_add(gen, 1u);
;         else { unsigned sp = 0; while (xb_ld(gen) == g) { __builtin_amdgcn_s_sleep(1); if (++sp > (1u << 22)) break; } }
;         __builtin_amdgcn_fence(__ATOMIC_ACQUIRE, "agent");
;         asm volatile("s_waitcnt vmcnt(0)" ::: "memory");
.Lxs0_done:
	buffer_inv sc0
	s_waitcnt vmcnt(0)
